# residual-add GEMM epilogues: 15 of 16 residual pieces prefetched into dead fragment registers, counted vmcnt, global stores
# speedup vs baseline: 1.0483x; 1.0039x over previous
; template <int EPI>
; DI void gemm_phase(const int wid_s, const h16* __restrict__ A, const h16* __restrict__ Bt, const int N, const int K, const EpiArgs ea) {
;     ...
;     for (int ai = 0; ai < 2; ++ai)
; #pragma unroll
;       for (int m = 0; m < 4; ++m) {
;         const size_t row = (size_t)(brow + ai * HALF + wr * 64 + m * 16 + fr);
; #pragma unroll
;         for (int bj = 0; bj < 2; ++bj) {
;           const int col0 = bcol + bj * HALF + wc * 32 + 8 * fq;
;           const f32x4 v0 = acc[ai][bj][m][0], v1 = acc[ai][bj][m][1];
;           if (EPI == 0) {
;             half8 o = {(h16)v0[0], (h16)v0[1], (h16)v0[2], (h16)v0[3], (h16)v1[0], (h16)v1[1], (h16)v1[2], (h16)v1[3]};
;             *(half8*)(ea.out + row * LDH + col0) = o;
;           } else if (EPI == 1) {
;             const half8 r = *(const half8*)(ea.res + row * 1024 + col0);
;             half8 o;
; #pragma unroll
;             for (int j = 0; j < 4; ++j) { o[j] = (h16)(ALPHA_F * (float)r[j] + v0[j]); o[4 + j] = (h16)(ALPHA_F * (float)r[4 + j] + v1[j]); }
;             *(half8*)(ea.out + row * 1024 + col0) = o;
.LBB0_125:
	v_add_u32_e32 v146, s39, v5
	v_or_b32_e32 v144, s40, v150
	v_ashrrev_i32_e32 v147, 31, v146
	v_lshlrev_b64 v[152:153], 11, v[146:147]
	v_ashrrev_i32_e32 v145, 31, v144
	v_lshl_add_u64 v[154:155], s[92:93], 0, v[152:153]
	v_lshlrev_b64 v[144:145], 1, v[144:145]
	v_lshl_add_u64 v[180:181], v[154:155], 0, v[144:145]
	v_lshl_add_u64 v[178:179], s[94:95], 0, v[152:153]
	global_load_dwordx4 v[186:189], v[180:181], off
	global_load_dwordx4 v[190:193], v[180:181], off offset:256
	v_add_co_u32_e32 v246, vcc, 0x8000, v180
	s_nop 1
	v_addc_co_u32_e32 v247, vcc, 0, v181, vcc
	global_load_dwordx4 v[194:197], v[246:247], off
	global_load_dwordx4 v[198:201], v[246:247], off offset:256
	v_add_co_u32_e32 v246, vcc, 0x10000, v180
	s_nop 1
	v_addc_co_u32_e32 v247, vcc, 0, v181, vcc
	global_load_dwordx4 v[202:205], v[246:247], off
	global_load_dwordx4 v[206:209], v[246:247], off offset:256
	v_add_co_u32_e32 v246, vcc, 0x18000, v180
	s_nop 1
	v_addc_co_u32_e32 v247, vcc, 0, v181, vcc
	global_load_dwordx4 v[210:213], v[246:247], off
	global_load_dwordx4 v[214:217], v[246:247], off offset:256
	v_add_co_u32_e32 v246, vcc, 0x40000, v180
	s_nop 1
	v_addc_co_u32_e32 v247, vcc, 0, v181, vcc
	global_load_dwordx4 v[218:221], v[246:247], off
	global_load_dwordx4 v[222:225], v[246:247], off offset:256
	v_add_co_u32_e32 v246, vcc, 0x48000, v180
	s_nop 1
	v_addc_co_u32_e32 v247, vcc, 0, v181, vcc
	global_load_dwordx4 v[226:229], v[246:247], off
	global_load_dwordx4 v[230:233], v[246:247], off offset:256
	v_add_co_u32_e32 v246, vcc, 0x50000, v180
	s_nop 1
	v_addc_co_u32_e32 v247, vcc, 0, v181, vcc
	global_load_dwordx4 v[234:237], v[246:247], off
	global_load_dwordx4 v[238:241], v[246:247], off offset:256
	v_add_co_u32_e32 v246, vcc, 0x58000, v180
	s_nop 1
	v_addc_co_u32_e32 v247, vcc, 0, v181, vcc
	global_load_dwordx4 v[242:245], v[246:247], off
	s_waitcnt vmcnt(13)
	v_cvt_f32_f16_e32 v182, v186
	v_cvt_f32_f16_sdwa v183, v186 dst_sel:DWORD dst_unused:UNUSED_PAD src0_sel:WORD_1
	v_pk_fma_f32 v[130:131], v[182:183], s[34:35], v[130:131] op_sel_hi:[1,0,1]
	s_nop 0
	v_cvt_pk_f16_f32 v152, v130, v131
	v_cvt_f32_f16_e32 v130, v188
	v_cvt_f32_f16_sdwa v131, v188 dst_sel:DWORD dst_unused:UNUSED_PAD src0_sel:WORD_1
	v_pk_fma_f32 v[126:127], v[130:131], s[34:35], v[126:127] op_sel_hi:[1,0,1]
	s_nop 0
	v_cvt_pk_f16_f32 v154, v126, v127
	v_cvt_f32_f16_e32 v126, v187
	v_cvt_f32_f16_sdwa v127, v187 dst_sel:DWORD dst_unused:UNUSED_PAD src0_sel:WORD_1
	v_lshl_add_u64 v[130:131], v[178:179], 0, v[144:145]
	v_pk_fma_f32 v[126:127], v[126:127], s[34:35], v[132:133] op_sel_hi:[1,0,1]
	s_nop 0
	v_cvt_pk_f16_f32 v153, v126, v127
	v_cvt_f32_f16_e32 v126, v189
	v_cvt_f32_f16_sdwa v127, v189 dst_sel:DWORD dst_unused:UNUSED_PAD src0_sel:WORD_1
	v_pk_fma_f32 v[126:127], v[126:127], s[34:35], v[128:129] op_sel_hi:[1,0,1]
	s_nop 0
	v_cvt_pk_f16_f32 v155, v126, v127
	s_waitcnt vmcnt(13)
	v_cvt_f32_f16_e32 v132, v190
	v_cvt_f32_f16_sdwa v133, v190 dst_sel:DWORD dst_unused:UNUSED_PAD src0_sel:WORD_1
	global_store_dwordx4 v[130:131], v[152:155], off
	v_pk_fma_f32 v[122:123], v[132:133], s[34:35], v[122:123] op_sel_hi:[1,0,1]
	s_nop 0
	v_cvt_pk_f16_f32 v126, v122, v123
	v_cvt_f32_f16_e32 v122, v192
	v_cvt_f32_f16_sdwa v123, v192 dst_sel:DWORD dst_unused:UNUSED_PAD src0_sel:WORD_1
	v_pk_fma_f32 v[118:119], v[122:123], s[34:35], v[118:119] op_sel_hi:[1,0,1]
	s_nop 0
	v_cvt_pk_f16_f32 v128, v118, v119
	v_cvt_f32_f16_e32 v118, v191
	v_cvt_f32_f16_sdwa v119, v191 dst_sel:DWORD dst_unused:UNUSED_PAD src0_sel:WORD_1
	v_pk_fma_f32 v[118:119], v[118:119], s[34:35], v[124:125] op_sel_hi:[1,0,1]
	s_nop 0
	v_cvt_pk_f16_f32 v127, v118, v119
	v_cvt_f32_f16_e32 v118, v193
	v_cvt_f32_f16_sdwa v119, v193 dst_sel:DWORD dst_unused:UNUSED_PAD src0_sel:WORD_1
	v_pk_fma_f32 v[118:119], v[118:119], s[34:35], v[120:121] op_sel_hi:[1,0,1]
	s_nop 0
	v_cvt_pk_f16_f32 v129, v118, v119
	global_store_dwordx4 v[130:131], v[126:129], off offset:256
	v_add_u32_e32 v118, 16, v146
	v_ashrrev_i32_e32 v119, 31, v118
	v_lshlrev_b64 v[118:119], 11, v[118:119]
	v_lshl_add_u64 v[120:121], s[92:93], 0, v[118:119]
	v_lshl_add_u64 v[124:125], v[120:121], 0, v[144:145]
	v_lshl_add_u64 v[122:123], s[94:95], 0, v[118:119]
	s_waitcnt vmcnt(13)
	v_cvt_f32_f16_e32 v126, v194
	v_cvt_f32_f16_sdwa v127, v194 dst_sel:DWORD dst_unused:UNUSED_PAD src0_sel:WORD_1
	v_pk_fma_f32 v[114:115], v[126:127], s[34:35], v[114:115] op_sel_hi:[1,0,1]
	s_nop 0
	v_cvt_pk_f16_f32 v118, v114, v115
	v_cvt_f32_f16_e32 v114, v196
	v_cvt_f32_f16_sdwa v115, v196 dst_sel:DWORD dst_unused:UNUSED_PAD src0_sel:WORD_1
	v_pk_fma_f32 v[110:111], v[114:115], s[34:35], v[110:111] op_sel_hi:[1,0,1]
	s_nop 0
	v_cvt_pk_f16_f32 v120, v110, v111
	v_cvt_f32_f16_e32 v110, v195
	v_cvt_f32_f16_sdwa v111, v195 dst_sel:DWORD dst_unused:UNUSED_PAD src0_sel:WORD_1
	v_lshl_add_u64 v[114:115], v[122:123], 0, v[144:145]
	v_pk_fma_f32 v[110:111], v[110:111], s[34:35], v[116:117] op_sel_hi:[1,0,1]
	s_nop 0
	v_cvt_pk_f16_f32 v119, v110, v111
	v_cvt_f32_f16_e32 v110, v197
	v_cvt_f32_f16_sdwa v111, v197 dst_sel:DWORD dst_unused:UNUSED_PAD src0_sel:WORD_1
	v_pk_fma_f32 v[110:111], v[110:111], s[34:35], v[112:113] op_sel_hi:[1,0,1]
	s_nop 0
	v_cvt_pk_f16_f32 v121, v110, v111
	s_waitcnt vmcnt(13)
; template <int EPI>
; DI void gemm_phase(const int wid_s, const h16* __restrict__ A, const h16* __restrict__ Bt, const int N, const int K, const EpiArgs ea) {
;     ...
;         const size_t row = (size_t)(brow + ai * HALF + wr * 64 + m * 16 + fr);
; #pragma unroll
;         for (int bj = 0; bj < 2; ++bj) {
;           const int col0 = bcol + bj * HALF + wc * 32 + 8 * fq;
;           const f32x4 v0 = acc[ai][bj][m][0], v1 = acc[ai][bj][m][1];
;           if (EPI == 0) {
;             half8 o = {(h16)v0[0], (h16)v0[1], (h16)v0[2], (h16)v0[3], (h16)v1[0], (h16)v1[1], (h16)v1[2], (h16)v1[3]};
;             *(half8*)(ea.out + row * LDH + col0) = o;
;           } else if (EPI == 1) {
;             const half8 r = *(const half8*)(ea.res + row * 1024 + col0);
;             half8 o;
; #pragma unroll
;             for (int j = 0; j < 4; ++j) { o[j] = (h16)(ALPHA_F * (float)r[j] + v0[j]); o[4 + j] = (h16)(ALPHA_F * (float)r[4 + j] + v1[j]); }
;             *(half8*)(ea.out + row * 1024 + col0) = o;
	v_cvt_f32_f16_e32 v116, v198
	v_cvt_f32_f16_sdwa v117, v198 dst_sel:DWORD dst_unused:UNUSED_PAD src0_sel:WORD_1
	global_store_dwordx4 v[114:115], v[118:121], off
	v_pk_fma_f32 v[106:107], v[116:117], s[34:35], v[106:107] op_sel_hi:[1,0,1]
	s_nop 0
	v_cvt_pk_f16_f32 v110, v106, v107
	v_cvt_f32_f16_e32 v106, v200
	v_cvt_f32_f16_sdwa v107, v200 dst_sel:DWORD dst_unused:UNUSED_PAD src0_sel:WORD_1
	v_pk_fma_f32 v[102:103], v[106:107], s[34:35], v[102:103] op_sel_hi:[1,0,1]
	s_nop 0
	v_cvt_pk_f16_f32 v112, v102, v103
	v_cvt_f32_f16_e32 v102, v199
	v_cvt_f32_f16_sdwa v103, v199 dst_sel:DWORD dst_unused:UNUSED_PAD src0_sel:WORD_1
	v_pk_fma_f32 v[102:103], v[102:103], s[34:35], v[108:109] op_sel_hi:[1,0,1]
	s_nop 0
	v_cvt_pk_f16_f32 v111, v102, v103
	v_cvt_f32_f16_e32 v102, v201
	v_cvt_f32_f16_sdwa v103, v201 dst_sel:DWORD dst_unused:UNUSED_PAD src0_sel:WORD_1
	v_pk_fma_f32 v[102:103], v[102:103], s[34:35], v[104:105] op_sel_hi:[1,0,1]
	s_nop 0
	v_cvt_pk_f16_f32 v113, v102, v103
	global_store_dwordx4 v[114:115], v[110:113], off offset:256
	v_add_u32_e32 v102, 32, v146
	v_ashrrev_i32_e32 v103, 31, v102
	v_lshlrev_b64 v[102:103], 11, v[102:103]
	v_lshl_add_u64 v[104:105], s[92:93], 0, v[102:103]
	v_lshl_add_u64 v[108:109], v[104:105], 0, v[144:145]
	v_lshl_add_u64 v[106:107], s[94:95], 0, v[102:103]
	s_waitcnt vmcnt(13)
	v_cvt_f32_f16_e32 v110, v202
	v_cvt_f32_f16_sdwa v111, v202 dst_sel:DWORD dst_unused:UNUSED_PAD src0_sel:WORD_1
	v_pk_fma_f32 v[98:99], v[110:111], s[34:35], v[98:99] op_sel_hi:[1,0,1]
	s_nop 0
	v_cvt_pk_f16_f32 v102, v98, v99
	v_cvt_f32_f16_e32 v98, v204
	v_cvt_f32_f16_sdwa v99, v204 dst_sel:DWORD dst_unused:UNUSED_PAD src0_sel:WORD_1
	v_pk_fma_f32 v[94:95], v[98:99], s[34:35], v[94:95] op_sel_hi:[1,0,1]
	s_nop 0
	v_cvt_pk_f16_f32 v104, v94, v95
	v_cvt_f32_f16_e32 v94, v203
	v_cvt_f32_f16_sdwa v95, v203 dst_sel:DWORD dst_unused:UNUSED_PAD src0_sel:WORD_1
	v_lshl_add_u64 v[98:99], v[106:107], 0, v[144:145]
	v_pk_fma_f32 v[94:95], v[94:95], s[34:35], v[100:101] op_sel_hi:[1,0,1]
	s_nop 0
	v_cvt_pk_f16_f32 v103, v94, v95
	v_cvt_f32_f16_e32 v94, v205
	v_cvt_f32_f16_sdwa v95, v205 dst_sel:DWORD dst_unused:UNUSED_PAD src0_sel:WORD_1
	v_pk_fma_f32 v[94:95], v[94:95], s[34:35], v[96:97] op_sel_hi:[1,0,1]
	s_nop 0
	v_cvt_pk_f16_f32 v105, v94, v95
	s_waitcnt vmcnt(13)
	v_cvt_f32_f16_e32 v100, v206
	v_cvt_f32_f16_sdwa v101, v206 dst_sel:DWORD dst_unused:UNUSED_PAD src0_sel:WORD_1
	global_store_dwordx4 v[98:99], v[102:105], off
	v_pk_fma_f32 v[90:91], v[100:101], s[34:35], v[90:91] op_sel_hi:[1,0,1]
	s_nop 0
	v_cvt_pk_f16_f32 v94, v90, v91
	v_cvt_f32_f16_e32 v90, v208
	v_cvt_f32_f16_sdwa v91, v208 dst_sel:DWORD dst_unused:UNUSED_PAD src0_sel:WORD_1
	v_pk_fma_f32 v[86:87], v[90:91], s[34:35], v[86:87] op_sel_hi:[1,0,1]
	s_nop 0
	v_cvt_pk_f16_f32 v96, v86, v87
	v_cvt_f32_f16_e32 v86, v207
	v_cvt_f32_f16_sdwa v87, v207 dst_sel:DWORD dst_unused:UNUSED_PAD src0_sel:WORD_1
	v_pk_fma_f32 v[86:87], v[86:87], s[34:35], v[92:93] op_sel_hi:[1,0,1]
	s_nop 0
	v_cvt_pk_f16_f32 v95, v86, v87
	v_cvt_f32_f16_e32 v86, v209
	v_cvt_f32_f16_sdwa v87, v209 dst_sel:DWORD dst_unused:UNUSED_PAD src0_sel:WORD_1
	v_pk_fma_f32 v[86:87], v[86:87], s[34:35], v[88:89] op_sel_hi:[1,0,1]
	s_nop 0
	v_cvt_pk_f16_f32 v97, v86, v87
	global_store_dwordx4 v[98:99], v[94:97], off offset:256
	v_add_u32_e32 v86, 48, v146
	v_ashrrev_i32_e32 v87, 31, v86
	v_lshlrev_b64 v[86:87], 11, v[86:87]
	v_lshl_add_u64 v[88:89], s[92:93], 0, v[86:87]
	v_lshl_add_u64 v[92:93], v[88:89], 0, v[144:145]
	v_lshl_add_u64 v[90:91], s[94:95], 0, v[86:87]
	s_waitcnt vmcnt(13)
	v_cvt_f32_f16_e32 v94, v210
	v_cvt_f32_f16_sdwa v95, v210 dst_sel:DWORD dst_unused:UNUSED_PAD src0_sel:WORD_1
	v_pk_fma_f32 v[82:83], v[94:95], s[34:35], v[82:83] op_sel_hi:[1,0,1]
	s_nop 0
	v_cvt_pk_f16_f32 v86, v82, v83
	v_cvt_f32_f16_e32 v82, v212
	v_cvt_f32_f16_sdwa v83, v212 dst_sel:DWORD dst_unused:UNUSED_PAD src0_sel:WORD_1
	v_pk_fma_f32 v[78:79], v[82:83], s[34:35], v[78:79] op_sel_hi:[1,0,1]
	s_nop 0
	v_cvt_pk_f16_f32 v88, v78, v79
	v_cvt_f32_f16_e32 v78, v211
	v_cvt_f32_f16_sdwa v79, v211 dst_sel:DWORD dst_unused:UNUSED_PAD src0_sel:WORD_1
	v_lshl_add_u64 v[82:83], v[90:91], 0, v[144:145]
	v_pk_fma_f32 v[78:79], v[78:79], s[34:35], v[84:85] op_sel_hi:[1,0,1]
	s_nop 0
	v_cvt_pk_f16_f32 v87, v78, v79
	v_cvt_f32_f16_e32 v78, v213
	v_cvt_f32_f16_sdwa v79, v213 dst_sel:DWORD dst_unused:UNUSED_PAD src0_sel:WORD_1
	v_pk_fma_f32 v[78:79], v[78:79], s[34:35], v[80:81] op_sel_hi:[1,0,1]
	s_nop 0
	v_cvt_pk_f16_f32 v89, v78, v79
	s_waitcnt vmcnt(13)
	v_cvt_f32_f16_e32 v84, v214
	v_cvt_f32_f16_sdwa v85, v214 dst_sel:DWORD dst_unused:UNUSED_PAD src0_sel:WORD_1
	global_store_dwordx4 v[82:83], v[86:89], off
	v_pk_fma_f32 v[74:75], v[84:85], s[34:35], v[74:75] op_sel_hi:[1,0,1]
	s_nop 0
	v_cvt_pk_f16_f32 v78, v74, v75
	v_cvt_f32_f16_e32 v74, v216
	v_cvt_f32_f16_sdwa v75, v216 dst_sel:DWORD dst_unused:UNUSED_PAD src0_sel:WORD_1
	v_pk_fma_f32 v[70:71], v[74:75], s[34:35], v[70:71] op_sel_hi:[1,0,1]
	s_nop 0
	v_cvt_pk_f16_f32 v80, v70, v71
	v_cvt_f32_f16_e32 v70, v215
	v_cvt_f32_f16_sdwa v71, v215 dst_sel:DWORD dst_unused:UNUSED_PAD src0_sel:WORD_1
	v_pk_fma_f32 v[70:71], v[70:71], s[34:35], v[76:77] op_sel_hi:[1,0,1]
	s_nop 0
	v_cvt_pk_f16_f32 v79, v70, v71
	v_cvt_f32_f16_e32 v70, v217
	v_cvt_f32_f16_sdwa v71, v217 dst_sel:DWORD dst_unused:UNUSED_PAD src0_sel:WORD_1
	v_pk_fma_f32 v[70:71], v[70:71], s[34:35], v[72:73] op_sel_hi:[1,0,1]
	s_nop 0
	v_cvt_pk_f16_f32 v81, v70, v71
	global_store_dwordx4 v[82:83], v[78:81], off offset:256
	v_add_u32_e32 v70, 0x80, v146
	v_ashrrev_i32_e32 v71, 31, v70
	v_lshlrev_b64 v[70:71], 11, v[70:71]
	v_lshl_add_u64 v[72:73], s[92:93], 0, v[70:71]
	v_lshl_add_u64 v[76:77], v[72:73], 0, v[144:145]
	v_lshl_add_u64 v[74:75], s[94:95], 0, v[70:71]
	s_waitcnt vmcnt(13)
; template <int EPI>
; DI void gemm_phase(const int wid_s, const h16* __restrict__ A, const h16* __restrict__ Bt, const int N, const int K, const EpiArgs ea) {
;     ...
;         const size_t row = (size_t)(brow + ai * HALF + wr * 64 + m * 16 + fr);
; #pragma unroll
;         for (int bj = 0; bj < 2; ++bj) {
;           const int col0 = bcol + bj * HALF + wc * 32 + 8 * fq;
;           const f32x4 v0 = acc[ai][bj][m][0], v1 = acc[ai][bj][m][1];
;           if (EPI == 0) {
;             half8 o = {(h16)v0[0], (h16)v0[1], (h16)v0[2], (h16)v0[3], (h16)v1[0], (h16)v1[1], (h16)v1[2], (h16)v1[3]};
;             *(half8*)(ea.out + row * LDH + col0) = o;
;           } else if (EPI == 1) {
;             const half8 r = *(const half8*)(ea.res + row * 1024 + col0);
;             half8 o;
; #pragma unroll
;             for (int j = 0; j < 4; ++j) { o[j] = (h16)(ALPHA_F * (float)r[j] + v0[j]); o[4 + j] = (h16)(ALPHA_F * (float)r[4 + j] + v1[j]); }
;             *(half8*)(ea.out + row * 1024 + col0) = o;
	v_cvt_f32_f16_e32 v78, v218
	v_cvt_f32_f16_sdwa v79, v218 dst_sel:DWORD dst_unused:UNUSED_PAD src0_sel:WORD_1
	v_pk_fma_f32 v[66:67], v[78:79], s[34:35], v[66:67] op_sel_hi:[1,0,1]
	s_nop 0
	v_cvt_pk_f16_f32 v70, v66, v67
	v_cvt_f32_f16_e32 v66, v220
	v_cvt_f32_f16_sdwa v67, v220 dst_sel:DWORD dst_unused:UNUSED_PAD src0_sel:WORD_1
	v_pk_fma_f32 v[62:63], v[66:67], s[34:35], v[62:63] op_sel_hi:[1,0,1]
	s_nop 0
	v_cvt_pk_f16_f32 v72, v62, v63
	v_cvt_f32_f16_e32 v62, v219
	v_cvt_f32_f16_sdwa v63, v219 dst_sel:DWORD dst_unused:UNUSED_PAD src0_sel:WORD_1
	v_lshl_add_u64 v[66:67], v[74:75], 0, v[144:145]
	v_pk_fma_f32 v[62:63], v[62:63], s[34:35], v[68:69] op_sel_hi:[1,0,1]
	s_nop 0
	v_cvt_pk_f16_f32 v71, v62, v63
	v_cvt_f32_f16_e32 v62, v221
	v_cvt_f32_f16_sdwa v63, v221 dst_sel:DWORD dst_unused:UNUSED_PAD src0_sel:WORD_1
	v_pk_fma_f32 v[62:63], v[62:63], s[34:35], v[64:65] op_sel_hi:[1,0,1]
	s_nop 0
	v_cvt_pk_f16_f32 v73, v62, v63
	s_waitcnt vmcnt(13)
	v_cvt_f32_f16_e32 v68, v222
	v_cvt_f32_f16_sdwa v69, v222 dst_sel:DWORD dst_unused:UNUSED_PAD src0_sel:WORD_1
	global_store_dwordx4 v[66:67], v[70:73], off
	v_pk_fma_f32 v[58:59], v[68:69], s[34:35], v[58:59] op_sel_hi:[1,0,1]
	s_nop 0
	v_cvt_pk_f16_f32 v62, v58, v59
	v_cvt_f32_f16_e32 v58, v224
	v_cvt_f32_f16_sdwa v59, v224 dst_sel:DWORD dst_unused:UNUSED_PAD src0_sel:WORD_1
	v_pk_fma_f32 v[54:55], v[58:59], s[34:35], v[54:55] op_sel_hi:[1,0,1]
	s_nop 0
	v_cvt_pk_f16_f32 v64, v54, v55
	v_cvt_f32_f16_e32 v54, v223
	v_cvt_f32_f16_sdwa v55, v223 dst_sel:DWORD dst_unused:UNUSED_PAD src0_sel:WORD_1
	v_pk_fma_f32 v[54:55], v[54:55], s[34:35], v[60:61] op_sel_hi:[1,0,1]
	s_nop 0
	v_cvt_pk_f16_f32 v63, v54, v55
	v_cvt_f32_f16_e32 v54, v225
	v_cvt_f32_f16_sdwa v55, v225 dst_sel:DWORD dst_unused:UNUSED_PAD src0_sel:WORD_1
	v_pk_fma_f32 v[54:55], v[54:55], s[34:35], v[56:57] op_sel_hi:[1,0,1]
	s_nop 0
	v_cvt_pk_f16_f32 v65, v54, v55
	global_store_dwordx4 v[66:67], v[62:65], off offset:256
	v_add_u32_e32 v54, 0x90, v146
	v_ashrrev_i32_e32 v55, 31, v54
	v_lshlrev_b64 v[54:55], 11, v[54:55]
	v_lshl_add_u64 v[56:57], s[92:93], 0, v[54:55]
	v_lshl_add_u64 v[60:61], v[56:57], 0, v[144:145]
	v_lshl_add_u64 v[58:59], s[94:95], 0, v[54:55]
	s_waitcnt vmcnt(13)
	v_cvt_f32_f16_e32 v62, v226
	v_cvt_f32_f16_sdwa v63, v226 dst_sel:DWORD dst_unused:UNUSED_PAD src0_sel:WORD_1
	v_pk_fma_f32 v[50:51], v[62:63], s[34:35], v[50:51] op_sel_hi:[1,0,1]
	s_nop 0
	v_cvt_pk_f16_f32 v54, v50, v51
	v_cvt_f32_f16_e32 v50, v228
	v_cvt_f32_f16_sdwa v51, v228 dst_sel:DWORD dst_unused:UNUSED_PAD src0_sel:WORD_1
	v_pk_fma_f32 v[46:47], v[50:51], s[34:35], v[46:47] op_sel_hi:[1,0,1]
	s_nop 0
	v_cvt_pk_f16_f32 v56, v46, v47
	v_cvt_f32_f16_e32 v46, v227
	v_cvt_f32_f16_sdwa v47, v227 dst_sel:DWORD dst_unused:UNUSED_PAD src0_sel:WORD_1
	v_lshl_add_u64 v[50:51], v[58:59], 0, v[144:145]
	v_pk_fma_f32 v[46:47], v[46:47], s[34:35], v[52:53] op_sel_hi:[1,0,1]
	s_nop 0
	v_cvt_pk_f16_f32 v55, v46, v47
	v_cvt_f32_f16_e32 v46, v229
	v_cvt_f32_f16_sdwa v47, v229 dst_sel:DWORD dst_unused:UNUSED_PAD src0_sel:WORD_1
	v_pk_fma_f32 v[46:47], v[46:47], s[34:35], v[48:49] op_sel_hi:[1,0,1]
	s_nop 0
	v_cvt_pk_f16_f32 v57, v46, v47
	s_waitcnt vmcnt(13)
	v_cvt_f32_f16_e32 v52, v230
	v_cvt_f32_f16_sdwa v53, v230 dst_sel:DWORD dst_unused:UNUSED_PAD src0_sel:WORD_1
	global_store_dwordx4 v[50:51], v[54:57], off
	v_pk_fma_f32 v[42:43], v[52:53], s[34:35], v[42:43] op_sel_hi:[1,0,1]
	s_nop 0
	v_cvt_pk_f16_f32 v46, v42, v43
	v_cvt_f32_f16_e32 v42, v232
	v_cvt_f32_f16_sdwa v43, v232 dst_sel:DWORD dst_unused:UNUSED_PAD src0_sel:WORD_1
	v_pk_fma_f32 v[38:39], v[42:43], s[34:35], v[38:39] op_sel_hi:[1,0,1]
	s_nop 0
	v_cvt_pk_f16_f32 v48, v38, v39
	v_cvt_f32_f16_e32 v38, v231
	v_cvt_f32_f16_sdwa v39, v231 dst_sel:DWORD dst_unused:UNUSED_PAD src0_sel:WORD_1
	v_pk_fma_f32 v[38:39], v[38:39], s[34:35], v[44:45] op_sel_hi:[1,0,1]
	s_nop 0
	v_cvt_pk_f16_f32 v47, v38, v39
	v_cvt_f32_f16_e32 v38, v233
	v_cvt_f32_f16_sdwa v39, v233 dst_sel:DWORD dst_unused:UNUSED_PAD src0_sel:WORD_1
	v_pk_fma_f32 v[38:39], v[38:39], s[34:35], v[40:41] op_sel_hi:[1,0,1]
	s_nop 0
	v_cvt_pk_f16_f32 v49, v38, v39
	global_store_dwordx4 v[50:51], v[46:49], off offset:256
	v_add_u32_e32 v38, 0xa0, v146
	v_ashrrev_i32_e32 v39, 31, v38
	v_lshlrev_b64 v[38:39], 11, v[38:39]
	v_lshl_add_u64 v[40:41], s[92:93], 0, v[38:39]
	v_lshl_add_u64 v[44:45], v[40:41], 0, v[144:145]
	v_lshl_add_u64 v[42:43], s[94:95], 0, v[38:39]
	s_waitcnt vmcnt(13)
; #define BAR __builtin_amdgcn_s_barrier()
; template <int EPI>
; DI void gemm_phase(const int wid_s, const h16* __restrict__ A, const h16* __restrict__ Bt, const int N, const int K, const EpiArgs ea) {
;     ...
;         const size_t row = (size_t)(brow + ai * HALF + wr * 64 + m * 16 + fr);
; #pragma unroll
;         for (int bj = 0; bj < 2; ++bj) {
;           const int col0 = bcol + bj * HALF + wc * 32 + 8 * fq;
;           const f32x4 v0 = acc[ai][bj][m][0], v1 = acc[ai][bj][m][1];
;           if (EPI == 0) {
;             half8 o = {(h16)v0[0], (h16)v0[1], (h16)v0[2], (h16)v0[3], (h16)v1[0], (h16)v1[1], (h16)v1[2], (h16)v1[3]};
;             *(half8*)(ea.out + row * LDH + col0) = o;
;           } else if (EPI == 1) {
;             const half8 r = *(const half8*)(ea.res + row * 1024 + col0);
;             half8 o;
; #pragma unroll
;             for (int j = 0; j < 4; ++j) { o[j] = (h16)(ALPHA_F * (float)r[j] + v0[j]); o[4 + j] = (h16)(ALPHA_F * (float)r[4 + j] + v1[j]); }
;             *(half8*)(ea.out + row * 1024 + col0) = o;
;     ...
;     if (!has_next) break;
; #pragma unroll
;     for (int a = 0; a < 2; ++a)
; #pragma unroll
;       for (int b = 0; b < 2; ++b)
; #pragma unroll
;         for (int m = 0; m < 4; ++m)
; #pragma unroll
;           for (int n = 0; n < 2; ++n) acc[a][b][m][n] = (f32x4){0.f, 0.f, 0.f, 0.f};
;     L = Ln; brow = nbrow; bcol = nbcol; cA = nA; cB = nB;
;     if (wr == 1) BAR;
	v_cvt_f32_f16_e32 v46, v234
	v_cvt_f32_f16_sdwa v47, v234 dst_sel:DWORD dst_unused:UNUSED_PAD src0_sel:WORD_1
	v_pk_fma_f32 v[34:35], v[46:47], s[34:35], v[34:35] op_sel_hi:[1,0,1]
	s_nop 0
	v_cvt_pk_f16_f32 v38, v34, v35
	v_cvt_f32_f16_e32 v34, v236
	v_cvt_f32_f16_sdwa v35, v236 dst_sel:DWORD dst_unused:UNUSED_PAD src0_sel:WORD_1
	v_pk_fma_f32 v[30:31], v[34:35], s[34:35], v[30:31] op_sel_hi:[1,0,1]
	s_nop 0
	v_cvt_pk_f16_f32 v40, v30, v31
	v_cvt_f32_f16_e32 v30, v235
	v_cvt_f32_f16_sdwa v31, v235 dst_sel:DWORD dst_unused:UNUSED_PAD src0_sel:WORD_1
	v_lshl_add_u64 v[34:35], v[42:43], 0, v[144:145]
	v_pk_fma_f32 v[30:31], v[30:31], s[34:35], v[36:37] op_sel_hi:[1,0,1]
	s_nop 0
	v_cvt_pk_f16_f32 v39, v30, v31
	v_cvt_f32_f16_e32 v30, v237
	v_cvt_f32_f16_sdwa v31, v237 dst_sel:DWORD dst_unused:UNUSED_PAD src0_sel:WORD_1
	v_pk_fma_f32 v[30:31], v[30:31], s[34:35], v[32:33] op_sel_hi:[1,0,1]
	s_nop 0
	v_cvt_pk_f16_f32 v41, v30, v31
	s_waitcnt vmcnt(13)
	v_cvt_f32_f16_e32 v36, v238
	v_cvt_f32_f16_sdwa v37, v238 dst_sel:DWORD dst_unused:UNUSED_PAD src0_sel:WORD_1
	global_store_dwordx4 v[34:35], v[38:41], off
	v_pk_fma_f32 v[26:27], v[36:37], s[34:35], v[26:27] op_sel_hi:[1,0,1]
	s_nop 0
	v_cvt_pk_f16_f32 v30, v26, v27
	v_cvt_f32_f16_e32 v26, v240
	v_cvt_f32_f16_sdwa v27, v240 dst_sel:DWORD dst_unused:UNUSED_PAD src0_sel:WORD_1
	v_pk_fma_f32 v[22:23], v[26:27], s[34:35], v[22:23] op_sel_hi:[1,0,1]
	s_nop 0
	v_cvt_pk_f16_f32 v32, v22, v23
	v_cvt_f32_f16_e32 v22, v239
	v_cvt_f32_f16_sdwa v23, v239 dst_sel:DWORD dst_unused:UNUSED_PAD src0_sel:WORD_1
	v_pk_fma_f32 v[22:23], v[22:23], s[34:35], v[28:29] op_sel_hi:[1,0,1]
	s_nop 0
	v_cvt_pk_f16_f32 v31, v22, v23
	v_cvt_f32_f16_e32 v22, v241
	v_cvt_f32_f16_sdwa v23, v241 dst_sel:DWORD dst_unused:UNUSED_PAD src0_sel:WORD_1
	v_pk_fma_f32 v[22:23], v[22:23], s[34:35], v[24:25] op_sel_hi:[1,0,1]
	s_nop 0
	v_cvt_pk_f16_f32 v33, v22, v23
	global_store_dwordx4 v[34:35], v[30:33], off offset:256
	v_add_u32_e32 v22, 0xb0, v146
	v_ashrrev_i32_e32 v23, 31, v22
	v_lshlrev_b64 v[22:23], 11, v[22:23]
	v_lshl_add_u64 v[24:25], s[92:93], 0, v[22:23]
	v_lshl_add_u64 v[28:29], v[24:25], 0, v[144:145]
	v_lshl_add_u64 v[26:27], s[94:95], 0, v[22:23]
	s_waitcnt vmcnt(13)
	v_cvt_f32_f16_e32 v30, v242
	v_cvt_f32_f16_sdwa v31, v242 dst_sel:DWORD dst_unused:UNUSED_PAD src0_sel:WORD_1
	v_pk_fma_f32 v[18:19], v[30:31], s[34:35], v[18:19] op_sel_hi:[1,0,1]
	s_nop 0
	v_cvt_pk_f16_f32 v22, v18, v19
	v_cvt_f32_f16_e32 v18, v244
	v_cvt_f32_f16_sdwa v19, v244 dst_sel:DWORD dst_unused:UNUSED_PAD src0_sel:WORD_1
	v_pk_fma_f32 v[14:15], v[18:19], s[34:35], v[14:15] op_sel_hi:[1,0,1]
	s_nop 0
	v_cvt_pk_f16_f32 v24, v14, v15
	v_cvt_f32_f16_e32 v14, v243
	v_cvt_f32_f16_sdwa v15, v243 dst_sel:DWORD dst_unused:UNUSED_PAD src0_sel:WORD_1
	v_lshl_add_u64 v[18:19], v[26:27], 0, v[144:145]
	v_pk_fma_f32 v[14:15], v[14:15], s[34:35], v[20:21] op_sel_hi:[1,0,1]
	s_nop 0
	v_cvt_pk_f16_f32 v23, v14, v15
	v_cvt_f32_f16_e32 v14, v245
	v_cvt_f32_f16_sdwa v15, v245 dst_sel:DWORD dst_unused:UNUSED_PAD src0_sel:WORD_1
	v_pk_fma_f32 v[14:15], v[14:15], s[34:35], v[16:17] op_sel_hi:[1,0,1]
	s_nop 0
	v_cvt_pk_f16_f32 v25, v14, v15
	global_load_dwordx4 v[14:17], v[28:29], off offset:256
	s_waitcnt vmcnt(0)
	v_cvt_f32_f16_e32 v20, v14
	v_cvt_f32_f16_sdwa v21, v14 dst_sel:DWORD dst_unused:UNUSED_PAD src0_sel:WORD_1
	global_store_dwordx4 v[18:19], v[22:25], off
	v_pk_fma_f32 v[10:11], v[20:21], s[34:35], v[10:11] op_sel_hi:[1,0,1]
	s_nop 0
	v_cvt_pk_f16_f32 v14, v10, v11
	v_cvt_f32_f16_e32 v10, v16
	v_cvt_f32_f16_sdwa v11, v16 dst_sel:DWORD dst_unused:UNUSED_PAD src0_sel:WORD_1
	v_pk_fma_f32 v[6:7], v[10:11], s[34:35], v[6:7] op_sel_hi:[1,0,1]
	s_nop 0
	v_cvt_pk_f16_f32 v16, v6, v7
	v_cvt_f32_f16_e32 v6, v15
	v_cvt_f32_f16_sdwa v7, v15 dst_sel:DWORD dst_unused:UNUSED_PAD src0_sel:WORD_1
	v_pk_fma_f32 v[6:7], v[6:7], s[34:35], v[12:13] op_sel_hi:[1,0,1]
	s_nop 0
	v_cvt_pk_f16_f32 v15, v6, v7
	v_cvt_f32_f16_e32 v6, v17
	v_cvt_f32_f16_sdwa v7, v17 dst_sel:DWORD dst_unused:UNUSED_PAD src0_sel:WORD_1
	v_pk_fma_f32 v[6:7], v[6:7], s[34:35], v[8:9] op_sel_hi:[1,0,1]
	s_nop 0
	v_cvt_pk_f16_f32 v17, v6, v7
	global_store_dwordx4 v[18:19], v[14:17], off offset:256
	s_andn2_b64 vcc, exec, s[6:7]
	s_mov_b64 s[6:7], -1
	s_cbranch_vccnz .LBB0_114
	s_andn2_b64 vcc, exec, s[0:1]
	s_cbranch_vccnz .LBB0_113
	s_barrier
	s_branch .LBB0_113

; template <int EPI>
; DI void gemm_phase(const int wid_s, const h16* __restrict__ A, const h16* __restrict__ Bt, const int N, const int K, const EpiArgs ea) {
;     ...
;         const size_t row = (size_t)(brow + ai * HALF + wr * 64 + m * 16 + fr);
; #pragma unroll
;         for (int bj = 0; bj < 2; ++bj) {
;           const int col0 = bcol + bj * HALF + wc * 32 + 8 * fq;
;           const f32x4 v0 = acc[ai][bj][m][0], v1 = acc[ai][bj][m][1];
;           if (EPI == 0) {
;             half8 o = {(h16)v0[0], (h16)v0[1], (h16)v0[2], (h16)v0[3], (h16)v1[0], (h16)v1[1], (h16)v1[2], (h16)v1[3]};
;             *(half8*)(ea.out + row * LDH + col0) = o;
;           } else if (EPI == 1) {
;             const half8 r = *(const half8*)(ea.res + row * 1024 + col0);
;             half8 o;
; #pragma unroll
;             for (int j = 0; j < 4; ++j) { o[j] = (h16)(ALPHA_F * (float)r[j] + v0[j]); o[4 + j] = (h16)(ALPHA_F * (float)r[4 + j] + v1[j]); }
;             *(half8*)(ea.out + row * 1024 + col0) = o;
.LBB0_178:
	v_add_u32_e32 v146, s16, v5
	v_or_b32_e32 v144, s18, v150
	v_ashrrev_i32_e32 v147, 31, v146
	v_lshlrev_b64 v[152:153], 11, v[146:147]
	v_ashrrev_i32_e32 v145, 31, v144
	v_lshl_add_u64 v[154:155], s[92:93], 0, v[152:153]
	v_lshlrev_b64 v[144:145], 1, v[144:145]
	v_lshl_add_u64 v[180:181], v[154:155], 0, v[144:145]
	v_lshl_add_u64 v[178:179], s[94:95], 0, v[152:153]
	global_load_dwordx4 v[186:189], v[180:181], off
	global_load_dwordx4 v[190:193], v[180:181], off offset:256
	v_add_co_u32_e32 v246, vcc, 0x8000, v180
	s_nop 1
	v_addc_co_u32_e32 v247, vcc, 0, v181, vcc
	global_load_dwordx4 v[194:197], v[246:247], off
	global_load_dwordx4 v[198:201], v[246:247], off offset:256
	v_add_co_u32_e32 v246, vcc, 0x10000, v180
	s_nop 1
	v_addc_co_u32_e32 v247, vcc, 0, v181, vcc
	global_load_dwordx4 v[202:205], v[246:247], off
	global_load_dwordx4 v[206:209], v[246:247], off offset:256
	v_add_co_u32_e32 v246, vcc, 0x18000, v180
	s_nop 1
	v_addc_co_u32_e32 v247, vcc, 0, v181, vcc
	global_load_dwordx4 v[210:213], v[246:247], off
	global_load_dwordx4 v[214:217], v[246:247], off offset:256
	v_add_co_u32_e32 v246, vcc, 0x40000, v180
	s_nop 1
	v_addc_co_u32_e32 v247, vcc, 0, v181, vcc
	global_load_dwordx4 v[218:221], v[246:247], off
	global_load_dwordx4 v[222:225], v[246:247], off offset:256
	v_add_co_u32_e32 v246, vcc, 0x48000, v180
	s_nop 1
	v_addc_co_u32_e32 v247, vcc, 0, v181, vcc
	global_load_dwordx4 v[226:229], v[246:247], off
	global_load_dwordx4 v[230:233], v[246:247], off offset:256
	v_add_co_u32_e32 v246, vcc, 0x50000, v180
	s_nop 1
	v_addc_co_u32_e32 v247, vcc, 0, v181, vcc
	global_load_dwordx4 v[234:237], v[246:247], off
	global_load_dwordx4 v[238:241], v[246:247], off offset:256
	v_add_co_u32_e32 v246, vcc, 0x58000, v180
	s_nop 1
	v_addc_co_u32_e32 v247, vcc, 0, v181, vcc
	global_load_dwordx4 v[242:245], v[246:247], off
	s_waitcnt vmcnt(13)
	v_cvt_f32_f16_e32 v182, v186
	v_cvt_f32_f16_sdwa v183, v186 dst_sel:DWORD dst_unused:UNUSED_PAD src0_sel:WORD_1
	v_pk_fma_f32 v[130:131], v[182:183], s[34:35], v[130:131] op_sel_hi:[1,0,1]
	s_nop 0
	v_cvt_pk_f16_f32 v152, v130, v131
	v_cvt_f32_f16_e32 v130, v188
	v_cvt_f32_f16_sdwa v131, v188 dst_sel:DWORD dst_unused:UNUSED_PAD src0_sel:WORD_1
	v_pk_fma_f32 v[126:127], v[130:131], s[34:35], v[126:127] op_sel_hi:[1,0,1]
	s_nop 0
	v_cvt_pk_f16_f32 v154, v126, v127
	v_cvt_f32_f16_e32 v126, v187
	v_cvt_f32_f16_sdwa v127, v187 dst_sel:DWORD dst_unused:UNUSED_PAD src0_sel:WORD_1
	v_lshl_add_u64 v[130:131], v[178:179], 0, v[144:145]
	v_pk_fma_f32 v[126:127], v[126:127], s[34:35], v[132:133] op_sel_hi:[1,0,1]
	s_nop 0
	v_cvt_pk_f16_f32 v153, v126, v127
	v_cvt_f32_f16_e32 v126, v189
	v_cvt_f32_f16_sdwa v127, v189 dst_sel:DWORD dst_unused:UNUSED_PAD src0_sel:WORD_1
	v_pk_fma_f32 v[126:127], v[126:127], s[34:35], v[128:129] op_sel_hi:[1,0,1]
	s_nop 0
	v_cvt_pk_f16_f32 v155, v126, v127
	s_waitcnt vmcnt(13)
	v_cvt_f32_f16_e32 v132, v190
	v_cvt_f32_f16_sdwa v133, v190 dst_sel:DWORD dst_unused:UNUSED_PAD src0_sel:WORD_1
	global_store_dwordx4 v[130:131], v[152:155], off
	v_pk_fma_f32 v[122:123], v[132:133], s[34:35], v[122:123] op_sel_hi:[1,0,1]
	s_nop 0
	v_cvt_pk_f16_f32 v126, v122, v123
	v_cvt_f32_f16_e32 v122, v192
	v_cvt_f32_f16_sdwa v123, v192 dst_sel:DWORD dst_unused:UNUSED_PAD src0_sel:WORD_1
	v_pk_fma_f32 v[118:119], v[122:123], s[34:35], v[118:119] op_sel_hi:[1,0,1]
	s_nop 0
	v_cvt_pk_f16_f32 v128, v118, v119
	v_cvt_f32_f16_e32 v118, v191
	v_cvt_f32_f16_sdwa v119, v191 dst_sel:DWORD dst_unused:UNUSED_PAD src0_sel:WORD_1
	v_pk_fma_f32 v[118:119], v[118:119], s[34:35], v[124:125] op_sel_hi:[1,0,1]
	s_nop 0
	v_cvt_pk_f16_f32 v127, v118, v119
	v_cvt_f32_f16_e32 v118, v193
	v_cvt_f32_f16_sdwa v119, v193 dst_sel:DWORD dst_unused:UNUSED_PAD src0_sel:WORD_1
	v_pk_fma_f32 v[118:119], v[118:119], s[34:35], v[120:121] op_sel_hi:[1,0,1]
	s_nop 0
	v_cvt_pk_f16_f32 v129, v118, v119
	global_store_dwordx4 v[130:131], v[126:129], off offset:256
	v_add_u32_e32 v118, 16, v146
	v_ashrrev_i32_e32 v119, 31, v118
	v_lshlrev_b64 v[118:119], 11, v[118:119]
	v_lshl_add_u64 v[120:121], s[92:93], 0, v[118:119]
	v_lshl_add_u64 v[124:125], v[120:121], 0, v[144:145]
	v_lshl_add_u64 v[122:123], s[94:95], 0, v[118:119]
	s_waitcnt vmcnt(13)
	v_cvt_f32_f16_e32 v126, v194
	v_cvt_f32_f16_sdwa v127, v194 dst_sel:DWORD dst_unused:UNUSED_PAD src0_sel:WORD_1
	v_pk_fma_f32 v[114:115], v[126:127], s[34:35], v[114:115] op_sel_hi:[1,0,1]
	s_nop 0
	v_cvt_pk_f16_f32 v118, v114, v115
	v_cvt_f32_f16_e32 v114, v196
	v_cvt_f32_f16_sdwa v115, v196 dst_sel:DWORD dst_unused:UNUSED_PAD src0_sel:WORD_1
	v_pk_fma_f32 v[110:111], v[114:115], s[34:35], v[110:111] op_sel_hi:[1,0,1]
	s_nop 0
	v_cvt_pk_f16_f32 v120, v110, v111
	v_cvt_f32_f16_e32 v110, v195
	v_cvt_f32_f16_sdwa v111, v195 dst_sel:DWORD dst_unused:UNUSED_PAD src0_sel:WORD_1
	v_lshl_add_u64 v[114:115], v[122:123], 0, v[144:145]
	v_pk_fma_f32 v[110:111], v[110:111], s[34:35], v[116:117] op_sel_hi:[1,0,1]
	s_nop 0
	v_cvt_pk_f16_f32 v119, v110, v111
	v_cvt_f32_f16_e32 v110, v197
	v_cvt_f32_f16_sdwa v111, v197 dst_sel:DWORD dst_unused:UNUSED_PAD src0_sel:WORD_1
	v_pk_fma_f32 v[110:111], v[110:111], s[34:35], v[112:113] op_sel_hi:[1,0,1]
	s_nop 0
	v_cvt_pk_f16_f32 v121, v110, v111
	s_waitcnt vmcnt(13)
; template <int EPI>
; DI void gemm_phase(const int wid_s, const h16* __restrict__ A, const h16* __restrict__ Bt, const int N, const int K, const EpiArgs ea) {
;     ...
;         const size_t row = (size_t)(brow + ai * HALF + wr * 64 + m * 16 + fr);
; #pragma unroll
;         for (int bj = 0; bj < 2; ++bj) {
;           const int col0 = bcol + bj * HALF + wc * 32 + 8 * fq;
;           const f32x4 v0 = acc[ai][bj][m][0], v1 = acc[ai][bj][m][1];
;           if (EPI == 0) {
;             half8 o = {(h16)v0[0], (h16)v0[1], (h16)v0[2], (h16)v0[3], (h16)v1[0], (h16)v1[1], (h16)v1[2], (h16)v1[3]};
;             *(half8*)(ea.out + row * LDH + col0) = o;
;           } else if (EPI == 1) {
;             const half8 r = *(const half8*)(ea.res + row * 1024 + col0);
;             half8 o;
; #pragma unroll
;             for (int j = 0; j < 4; ++j) { o[j] = (h16)(ALPHA_F * (float)r[j] + v0[j]); o[4 + j] = (h16)(ALPHA_F * (float)r[4 + j] + v1[j]); }
;             *(half8*)(ea.out + row * 1024 + col0) = o;
	v_cvt_f32_f16_e32 v116, v198
	v_cvt_f32_f16_sdwa v117, v198 dst_sel:DWORD dst_unused:UNUSED_PAD src0_sel:WORD_1
	global_store_dwordx4 v[114:115], v[118:121], off
	v_pk_fma_f32 v[106:107], v[116:117], s[34:35], v[106:107] op_sel_hi:[1,0,1]
	s_nop 0
	v_cvt_pk_f16_f32 v110, v106, v107
	v_cvt_f32_f16_e32 v106, v200
	v_cvt_f32_f16_sdwa v107, v200 dst_sel:DWORD dst_unused:UNUSED_PAD src0_sel:WORD_1
	v_pk_fma_f32 v[102:103], v[106:107], s[34:35], v[102:103] op_sel_hi:[1,0,1]
	s_nop 0
	v_cvt_pk_f16_f32 v112, v102, v103
	v_cvt_f32_f16_e32 v102, v199
	v_cvt_f32_f16_sdwa v103, v199 dst_sel:DWORD dst_unused:UNUSED_PAD src0_sel:WORD_1
	v_pk_fma_f32 v[102:103], v[102:103], s[34:35], v[108:109] op_sel_hi:[1,0,1]
	s_nop 0
	v_cvt_pk_f16_f32 v111, v102, v103
	v_cvt_f32_f16_e32 v102, v201
	v_cvt_f32_f16_sdwa v103, v201 dst_sel:DWORD dst_unused:UNUSED_PAD src0_sel:WORD_1
	v_pk_fma_f32 v[102:103], v[102:103], s[34:35], v[104:105] op_sel_hi:[1,0,1]
	s_nop 0
	v_cvt_pk_f16_f32 v113, v102, v103
	global_store_dwordx4 v[114:115], v[110:113], off offset:256
	v_add_u32_e32 v102, 32, v146
	v_ashrrev_i32_e32 v103, 31, v102
	v_lshlrev_b64 v[102:103], 11, v[102:103]
	v_lshl_add_u64 v[104:105], s[92:93], 0, v[102:103]
	v_lshl_add_u64 v[108:109], v[104:105], 0, v[144:145]
	v_lshl_add_u64 v[106:107], s[94:95], 0, v[102:103]
	s_waitcnt vmcnt(13)
	v_cvt_f32_f16_e32 v110, v202
	v_cvt_f32_f16_sdwa v111, v202 dst_sel:DWORD dst_unused:UNUSED_PAD src0_sel:WORD_1
	v_pk_fma_f32 v[98:99], v[110:111], s[34:35], v[98:99] op_sel_hi:[1,0,1]
	s_nop 0
	v_cvt_pk_f16_f32 v102, v98, v99
	v_cvt_f32_f16_e32 v98, v204
	v_cvt_f32_f16_sdwa v99, v204 dst_sel:DWORD dst_unused:UNUSED_PAD src0_sel:WORD_1
	v_pk_fma_f32 v[94:95], v[98:99], s[34:35], v[94:95] op_sel_hi:[1,0,1]
	s_nop 0
	v_cvt_pk_f16_f32 v104, v94, v95
	v_cvt_f32_f16_e32 v94, v203
	v_cvt_f32_f16_sdwa v95, v203 dst_sel:DWORD dst_unused:UNUSED_PAD src0_sel:WORD_1
	v_lshl_add_u64 v[98:99], v[106:107], 0, v[144:145]
	v_pk_fma_f32 v[94:95], v[94:95], s[34:35], v[100:101] op_sel_hi:[1,0,1]
	s_nop 0
	v_cvt_pk_f16_f32 v103, v94, v95
	v_cvt_f32_f16_e32 v94, v205
	v_cvt_f32_f16_sdwa v95, v205 dst_sel:DWORD dst_unused:UNUSED_PAD src0_sel:WORD_1
	v_pk_fma_f32 v[94:95], v[94:95], s[34:35], v[96:97] op_sel_hi:[1,0,1]
	s_nop 0
	v_cvt_pk_f16_f32 v105, v94, v95
	s_waitcnt vmcnt(13)
	v_cvt_f32_f16_e32 v100, v206
	v_cvt_f32_f16_sdwa v101, v206 dst_sel:DWORD dst_unused:UNUSED_PAD src0_sel:WORD_1
	global_store_dwordx4 v[98:99], v[102:105], off
	v_pk_fma_f32 v[90:91], v[100:101], s[34:35], v[90:91] op_sel_hi:[1,0,1]
	s_nop 0
	v_cvt_pk_f16_f32 v94, v90, v91
	v_cvt_f32_f16_e32 v90, v208
	v_cvt_f32_f16_sdwa v91, v208 dst_sel:DWORD dst_unused:UNUSED_PAD src0_sel:WORD_1
	v_pk_fma_f32 v[86:87], v[90:91], s[34:35], v[86:87] op_sel_hi:[1,0,1]
	s_nop 0
	v_cvt_pk_f16_f32 v96, v86, v87
	v_cvt_f32_f16_e32 v86, v207
	v_cvt_f32_f16_sdwa v87, v207 dst_sel:DWORD dst_unused:UNUSED_PAD src0_sel:WORD_1
	v_pk_fma_f32 v[86:87], v[86:87], s[34:35], v[92:93] op_sel_hi:[1,0,1]
	s_nop 0
	v_cvt_pk_f16_f32 v95, v86, v87
	v_cvt_f32_f16_e32 v86, v209
	v_cvt_f32_f16_sdwa v87, v209 dst_sel:DWORD dst_unused:UNUSED_PAD src0_sel:WORD_1
	v_pk_fma_f32 v[86:87], v[86:87], s[34:35], v[88:89] op_sel_hi:[1,0,1]
	s_nop 0
	v_cvt_pk_f16_f32 v97, v86, v87
	global_store_dwordx4 v[98:99], v[94:97], off offset:256
	v_add_u32_e32 v86, 48, v146
	v_ashrrev_i32_e32 v87, 31, v86
	v_lshlrev_b64 v[86:87], 11, v[86:87]
	v_lshl_add_u64 v[88:89], s[92:93], 0, v[86:87]
	v_lshl_add_u64 v[92:93], v[88:89], 0, v[144:145]
	v_lshl_add_u64 v[90:91], s[94:95], 0, v[86:87]
	s_waitcnt vmcnt(13)
	v_cvt_f32_f16_e32 v94, v210
	v_cvt_f32_f16_sdwa v95, v210 dst_sel:DWORD dst_unused:UNUSED_PAD src0_sel:WORD_1
	v_pk_fma_f32 v[82:83], v[94:95], s[34:35], v[82:83] op_sel_hi:[1,0,1]
	s_nop 0
	v_cvt_pk_f16_f32 v86, v82, v83
	v_cvt_f32_f16_e32 v82, v212
	v_cvt_f32_f16_sdwa v83, v212 dst_sel:DWORD dst_unused:UNUSED_PAD src0_sel:WORD_1
	v_pk_fma_f32 v[78:79], v[82:83], s[34:35], v[78:79] op_sel_hi:[1,0,1]
	s_nop 0
	v_cvt_pk_f16_f32 v88, v78, v79
	v_cvt_f32_f16_e32 v78, v211
	v_cvt_f32_f16_sdwa v79, v211 dst_sel:DWORD dst_unused:UNUSED_PAD src0_sel:WORD_1
	v_lshl_add_u64 v[82:83], v[90:91], 0, v[144:145]
	v_pk_fma_f32 v[78:79], v[78:79], s[34:35], v[84:85] op_sel_hi:[1,0,1]
	s_nop 0
	v_cvt_pk_f16_f32 v87, v78, v79
	v_cvt_f32_f16_e32 v78, v213
	v_cvt_f32_f16_sdwa v79, v213 dst_sel:DWORD dst_unused:UNUSED_PAD src0_sel:WORD_1
	v_pk_fma_f32 v[78:79], v[78:79], s[34:35], v[80:81] op_sel_hi:[1,0,1]
	s_nop 0
	v_cvt_pk_f16_f32 v89, v78, v79
	s_waitcnt vmcnt(13)
	v_cvt_f32_f16_e32 v84, v214
	v_cvt_f32_f16_sdwa v85, v214 dst_sel:DWORD dst_unused:UNUSED_PAD src0_sel:WORD_1
	global_store_dwordx4 v[82:83], v[86:89], off
	v_pk_fma_f32 v[74:75], v[84:85], s[34:35], v[74:75] op_sel_hi:[1,0,1]
	s_nop 0
	v_cvt_pk_f16_f32 v78, v74, v75
	v_cvt_f32_f16_e32 v74, v216
	v_cvt_f32_f16_sdwa v75, v216 dst_sel:DWORD dst_unused:UNUSED_PAD src0_sel:WORD_1
	v_pk_fma_f32 v[70:71], v[74:75], s[34:35], v[70:71] op_sel_hi:[1,0,1]
	s_nop 0
	v_cvt_pk_f16_f32 v80, v70, v71
	v_cvt_f32_f16_e32 v70, v215
	v_cvt_f32_f16_sdwa v71, v215 dst_sel:DWORD dst_unused:UNUSED_PAD src0_sel:WORD_1
	v_pk_fma_f32 v[70:71], v[70:71], s[34:35], v[76:77] op_sel_hi:[1,0,1]
	s_nop 0
	v_cvt_pk_f16_f32 v79, v70, v71
	v_cvt_f32_f16_e32 v70, v217
	v_cvt_f32_f16_sdwa v71, v217 dst_sel:DWORD dst_unused:UNUSED_PAD src0_sel:WORD_1
	v_pk_fma_f32 v[70:71], v[70:71], s[34:35], v[72:73] op_sel_hi:[1,0,1]
	s_nop 0
	v_cvt_pk_f16_f32 v81, v70, v71
	global_store_dwordx4 v[82:83], v[78:81], off offset:256
	v_add_u32_e32 v70, 0x80, v146
	v_ashrrev_i32_e32 v71, 31, v70
	v_lshlrev_b64 v[70:71], 11, v[70:71]
	v_lshl_add_u64 v[72:73], s[92:93], 0, v[70:71]
	v_lshl_add_u64 v[76:77], v[72:73], 0, v[144:145]
	v_lshl_add_u64 v[74:75], s[94:95], 0, v[70:71]
	s_waitcnt vmcnt(13)
; template <int EPI>
; DI void gemm_phase(const int wid_s, const h16* __restrict__ A, const h16* __restrict__ Bt, const int N, const int K, const EpiArgs ea) {
;     ...
;         const size_t row = (size_t)(brow + ai * HALF + wr * 64 + m * 16 + fr);
; #pragma unroll
;         for (int bj = 0; bj < 2; ++bj) {
;           const int col0 = bcol + bj * HALF + wc * 32 + 8 * fq;
;           const f32x4 v0 = acc[ai][bj][m][0], v1 = acc[ai][bj][m][1];
;           if (EPI == 0) {
;             half8 o = {(h16)v0[0], (h16)v0[1], (h16)v0[2], (h16)v0[3], (h16)v1[0], (h16)v1[1], (h16)v1[2], (h16)v1[3]};
;             *(half8*)(ea.out + row * LDH + col0) = o;
;           } else if (EPI == 1) {
;             const half8 r = *(const half8*)(ea.res + row * 1024 + col0);
;             half8 o;
; #pragma unroll
;             for (int j = 0; j < 4; ++j) { o[j] = (h16)(ALPHA_F * (float)r[j] + v0[j]); o[4 + j] = (h16)(ALPHA_F * (float)r[4 + j] + v1[j]); }
;             *(half8*)(ea.out + row * 1024 + col0) = o;
	v_cvt_f32_f16_e32 v78, v218
	v_cvt_f32_f16_sdwa v79, v218 dst_sel:DWORD dst_unused:UNUSED_PAD src0_sel:WORD_1
	v_pk_fma_f32 v[66:67], v[78:79], s[34:35], v[66:67] op_sel_hi:[1,0,1]
	s_nop 0
	v_cvt_pk_f16_f32 v70, v66, v67
	v_cvt_f32_f16_e32 v66, v220
	v_cvt_f32_f16_sdwa v67, v220 dst_sel:DWORD dst_unused:UNUSED_PAD src0_sel:WORD_1
	v_pk_fma_f32 v[62:63], v[66:67], s[34:35], v[62:63] op_sel_hi:[1,0,1]
	s_nop 0
	v_cvt_pk_f16_f32 v72, v62, v63
	v_cvt_f32_f16_e32 v62, v219
	v_cvt_f32_f16_sdwa v63, v219 dst_sel:DWORD dst_unused:UNUSED_PAD src0_sel:WORD_1
	v_lshl_add_u64 v[66:67], v[74:75], 0, v[144:145]
	v_pk_fma_f32 v[62:63], v[62:63], s[34:35], v[68:69] op_sel_hi:[1,0,1]
	s_nop 0
	v_cvt_pk_f16_f32 v71, v62, v63
	v_cvt_f32_f16_e32 v62, v221
	v_cvt_f32_f16_sdwa v63, v221 dst_sel:DWORD dst_unused:UNUSED_PAD src0_sel:WORD_1
	v_pk_fma_f32 v[62:63], v[62:63], s[34:35], v[64:65] op_sel_hi:[1,0,1]
	s_nop 0
	v_cvt_pk_f16_f32 v73, v62, v63
	s_waitcnt vmcnt(13)
	v_cvt_f32_f16_e32 v68, v222
	v_cvt_f32_f16_sdwa v69, v222 dst_sel:DWORD dst_unused:UNUSED_PAD src0_sel:WORD_1
	global_store_dwordx4 v[66:67], v[70:73], off
	v_pk_fma_f32 v[58:59], v[68:69], s[34:35], v[58:59] op_sel_hi:[1,0,1]
	s_nop 0
	v_cvt_pk_f16_f32 v62, v58, v59
	v_cvt_f32_f16_e32 v58, v224
	v_cvt_f32_f16_sdwa v59, v224 dst_sel:DWORD dst_unused:UNUSED_PAD src0_sel:WORD_1
	v_pk_fma_f32 v[54:55], v[58:59], s[34:35], v[54:55] op_sel_hi:[1,0,1]
	s_nop 0
	v_cvt_pk_f16_f32 v64, v54, v55
	v_cvt_f32_f16_e32 v54, v223
	v_cvt_f32_f16_sdwa v55, v223 dst_sel:DWORD dst_unused:UNUSED_PAD src0_sel:WORD_1
	v_pk_fma_f32 v[54:55], v[54:55], s[34:35], v[60:61] op_sel_hi:[1,0,1]
	s_nop 0
	v_cvt_pk_f16_f32 v63, v54, v55
	v_cvt_f32_f16_e32 v54, v225
	v_cvt_f32_f16_sdwa v55, v225 dst_sel:DWORD dst_unused:UNUSED_PAD src0_sel:WORD_1
	v_pk_fma_f32 v[54:55], v[54:55], s[34:35], v[56:57] op_sel_hi:[1,0,1]
	s_nop 0
	v_cvt_pk_f16_f32 v65, v54, v55
	global_store_dwordx4 v[66:67], v[62:65], off offset:256
	v_add_u32_e32 v54, 0x90, v146
	v_ashrrev_i32_e32 v55, 31, v54
	v_lshlrev_b64 v[54:55], 11, v[54:55]
	v_lshl_add_u64 v[56:57], s[92:93], 0, v[54:55]
	v_lshl_add_u64 v[60:61], v[56:57], 0, v[144:145]
	v_lshl_add_u64 v[58:59], s[94:95], 0, v[54:55]
	s_waitcnt vmcnt(13)
	v_cvt_f32_f16_e32 v62, v226
	v_cvt_f32_f16_sdwa v63, v226 dst_sel:DWORD dst_unused:UNUSED_PAD src0_sel:WORD_1
	v_pk_fma_f32 v[50:51], v[62:63], s[34:35], v[50:51] op_sel_hi:[1,0,1]
	s_nop 0
	v_cvt_pk_f16_f32 v54, v50, v51
	v_cvt_f32_f16_e32 v50, v228
	v_cvt_f32_f16_sdwa v51, v228 dst_sel:DWORD dst_unused:UNUSED_PAD src0_sel:WORD_1
	v_pk_fma_f32 v[46:47], v[50:51], s[34:35], v[46:47] op_sel_hi:[1,0,1]
	s_nop 0
	v_cvt_pk_f16_f32 v56, v46, v47
	v_cvt_f32_f16_e32 v46, v227
	v_cvt_f32_f16_sdwa v47, v227 dst_sel:DWORD dst_unused:UNUSED_PAD src0_sel:WORD_1
	v_lshl_add_u64 v[50:51], v[58:59], 0, v[144:145]
	v_pk_fma_f32 v[46:47], v[46:47], s[34:35], v[52:53] op_sel_hi:[1,0,1]
	s_nop 0
	v_cvt_pk_f16_f32 v55, v46, v47
	v_cvt_f32_f16_e32 v46, v229
	v_cvt_f32_f16_sdwa v47, v229 dst_sel:DWORD dst_unused:UNUSED_PAD src0_sel:WORD_1
	v_pk_fma_f32 v[46:47], v[46:47], s[34:35], v[48:49] op_sel_hi:[1,0,1]
	s_nop 0
	v_cvt_pk_f16_f32 v57, v46, v47
	s_waitcnt vmcnt(13)
	v_cvt_f32_f16_e32 v52, v230
	v_cvt_f32_f16_sdwa v53, v230 dst_sel:DWORD dst_unused:UNUSED_PAD src0_sel:WORD_1
	global_store_dwordx4 v[50:51], v[54:57], off
	v_pk_fma_f32 v[42:43], v[52:53], s[34:35], v[42:43] op_sel_hi:[1,0,1]
	s_nop 0
	v_cvt_pk_f16_f32 v46, v42, v43
	v_cvt_f32_f16_e32 v42, v232
	v_cvt_f32_f16_sdwa v43, v232 dst_sel:DWORD dst_unused:UNUSED_PAD src0_sel:WORD_1
	v_pk_fma_f32 v[38:39], v[42:43], s[34:35], v[38:39] op_sel_hi:[1,0,1]
	s_nop 0
	v_cvt_pk_f16_f32 v48, v38, v39
	v_cvt_f32_f16_e32 v38, v231
	v_cvt_f32_f16_sdwa v39, v231 dst_sel:DWORD dst_unused:UNUSED_PAD src0_sel:WORD_1
	v_pk_fma_f32 v[38:39], v[38:39], s[34:35], v[44:45] op_sel_hi:[1,0,1]
	s_nop 0
	v_cvt_pk_f16_f32 v47, v38, v39
	v_cvt_f32_f16_e32 v38, v233
	v_cvt_f32_f16_sdwa v39, v233 dst_sel:DWORD dst_unused:UNUSED_PAD src0_sel:WORD_1
	v_pk_fma_f32 v[38:39], v[38:39], s[34:35], v[40:41] op_sel_hi:[1,0,1]
	s_nop 0
	v_cvt_pk_f16_f32 v49, v38, v39
	global_store_dwordx4 v[50:51], v[46:49], off offset:256
	v_add_u32_e32 v38, 0xa0, v146
	v_ashrrev_i32_e32 v39, 31, v38
	v_lshlrev_b64 v[38:39], 11, v[38:39]
	v_lshl_add_u64 v[40:41], s[92:93], 0, v[38:39]
	v_lshl_add_u64 v[44:45], v[40:41], 0, v[144:145]
	v_lshl_add_u64 v[42:43], s[94:95], 0, v[38:39]
	s_waitcnt vmcnt(13)
; #define BAR __builtin_amdgcn_s_barrier()
; template <int EPI>
; DI void gemm_phase(const int wid_s, const h16* __restrict__ A, const h16* __restrict__ Bt, const int N, const int K, const EpiArgs ea) {
;     ...
;         const size_t row = (size_t)(brow + ai * HALF + wr * 64 + m * 16 + fr);
; #pragma unroll
;         for (int bj = 0; bj < 2; ++bj) {
;           const int col0 = bcol + bj * HALF + wc * 32 + 8 * fq;
;           const f32x4 v0 = acc[ai][bj][m][0], v1 = acc[ai][bj][m][1];
;           if (EPI == 0) {
;             half8 o = {(h16)v0[0], (h16)v0[1], (h16)v0[2], (h16)v0[3], (h16)v1[0], (h16)v1[1], (h16)v1[2], (h16)v1[3]};
;             *(half8*)(ea.out + row * LDH + col0) = o;
;           } else if (EPI == 1) {
;             const half8 r = *(const half8*)(ea.res + row * 1024 + col0);
;             half8 o;
; #pragma unroll
;             for (int j = 0; j < 4; ++j) { o[j] = (h16)(ALPHA_F * (float)r[j] + v0[j]); o[4 + j] = (h16)(ALPHA_F * (float)r[4 + j] + v1[j]); }
;             *(half8*)(ea.out + row * 1024 + col0) = o;
;     ...
;     if (!has_next) break;
; #pragma unroll
;     for (int a = 0; a < 2; ++a)
; #pragma unroll
;       for (int b = 0; b < 2; ++b)
; #pragma unroll
;         for (int m = 0; m < 4; ++m)
; #pragma unroll
;           for (int n = 0; n < 2; ++n) acc[a][b][m][n] = (f32x4){0.f, 0.f, 0.f, 0.f};
;     L = Ln; brow = nbrow; bcol = nbcol; cA = nA; cB = nB;
;     if (wr == 1) BAR;
	v_cvt_f32_f16_e32 v46, v234
	v_cvt_f32_f16_sdwa v47, v234 dst_sel:DWORD dst_unused:UNUSED_PAD src0_sel:WORD_1
	v_pk_fma_f32 v[34:35], v[46:47], s[34:35], v[34:35] op_sel_hi:[1,0,1]
	s_nop 0
	v_cvt_pk_f16_f32 v38, v34, v35
	v_cvt_f32_f16_e32 v34, v236
	v_cvt_f32_f16_sdwa v35, v236 dst_sel:DWORD dst_unused:UNUSED_PAD src0_sel:WORD_1
	v_pk_fma_f32 v[30:31], v[34:35], s[34:35], v[30:31] op_sel_hi:[1,0,1]
	s_nop 0
	v_cvt_pk_f16_f32 v40, v30, v31
	v_cvt_f32_f16_e32 v30, v235
	v_cvt_f32_f16_sdwa v31, v235 dst_sel:DWORD dst_unused:UNUSED_PAD src0_sel:WORD_1
	v_lshl_add_u64 v[34:35], v[42:43], 0, v[144:145]
	v_pk_fma_f32 v[30:31], v[30:31], s[34:35], v[36:37] op_sel_hi:[1,0,1]
	s_nop 0
	v_cvt_pk_f16_f32 v39, v30, v31
	v_cvt_f32_f16_e32 v30, v237
	v_cvt_f32_f16_sdwa v31, v237 dst_sel:DWORD dst_unused:UNUSED_PAD src0_sel:WORD_1
	v_pk_fma_f32 v[30:31], v[30:31], s[34:35], v[32:33] op_sel_hi:[1,0,1]
	s_nop 0
	v_cvt_pk_f16_f32 v41, v30, v31
	s_waitcnt vmcnt(13)
	v_cvt_f32_f16_e32 v36, v238
	v_cvt_f32_f16_sdwa v37, v238 dst_sel:DWORD dst_unused:UNUSED_PAD src0_sel:WORD_1
	global_store_dwordx4 v[34:35], v[38:41], off
	v_pk_fma_f32 v[26:27], v[36:37], s[34:35], v[26:27] op_sel_hi:[1,0,1]
	s_nop 0
	v_cvt_pk_f16_f32 v30, v26, v27
	v_cvt_f32_f16_e32 v26, v240
	v_cvt_f32_f16_sdwa v27, v240 dst_sel:DWORD dst_unused:UNUSED_PAD src0_sel:WORD_1
	v_pk_fma_f32 v[22:23], v[26:27], s[34:35], v[22:23] op_sel_hi:[1,0,1]
	s_nop 0
	v_cvt_pk_f16_f32 v32, v22, v23
	v_cvt_f32_f16_e32 v22, v239
	v_cvt_f32_f16_sdwa v23, v239 dst_sel:DWORD dst_unused:UNUSED_PAD src0_sel:WORD_1
	v_pk_fma_f32 v[22:23], v[22:23], s[34:35], v[28:29] op_sel_hi:[1,0,1]
	s_nop 0
	v_cvt_pk_f16_f32 v31, v22, v23
	v_cvt_f32_f16_e32 v22, v241
	v_cvt_f32_f16_sdwa v23, v241 dst_sel:DWORD dst_unused:UNUSED_PAD src0_sel:WORD_1
	v_pk_fma_f32 v[22:23], v[22:23], s[34:35], v[24:25] op_sel_hi:[1,0,1]
	s_nop 0
	v_cvt_pk_f16_f32 v33, v22, v23
	global_store_dwordx4 v[34:35], v[30:33], off offset:256
	v_add_u32_e32 v22, 0xb0, v146
	v_ashrrev_i32_e32 v23, 31, v22
	v_lshlrev_b64 v[22:23], 11, v[22:23]
	v_lshl_add_u64 v[24:25], s[92:93], 0, v[22:23]
	v_lshl_add_u64 v[28:29], v[24:25], 0, v[144:145]
	v_lshl_add_u64 v[26:27], s[94:95], 0, v[22:23]
	s_waitcnt vmcnt(13)
	v_cvt_f32_f16_e32 v30, v242
	v_cvt_f32_f16_sdwa v31, v242 dst_sel:DWORD dst_unused:UNUSED_PAD src0_sel:WORD_1
	v_pk_fma_f32 v[18:19], v[30:31], s[34:35], v[18:19] op_sel_hi:[1,0,1]
	s_nop 0
	v_cvt_pk_f16_f32 v22, v18, v19
	v_cvt_f32_f16_e32 v18, v244
	v_cvt_f32_f16_sdwa v19, v244 dst_sel:DWORD dst_unused:UNUSED_PAD src0_sel:WORD_1
	v_pk_fma_f32 v[14:15], v[18:19], s[34:35], v[14:15] op_sel_hi:[1,0,1]
	s_nop 0
	v_cvt_pk_f16_f32 v24, v14, v15
	v_cvt_f32_f16_e32 v14, v243
	v_cvt_f32_f16_sdwa v15, v243 dst_sel:DWORD dst_unused:UNUSED_PAD src0_sel:WORD_1
	v_lshl_add_u64 v[18:19], v[26:27], 0, v[144:145]
	v_pk_fma_f32 v[14:15], v[14:15], s[34:35], v[20:21] op_sel_hi:[1,0,1]
	s_nop 0
	v_cvt_pk_f16_f32 v23, v14, v15
	v_cvt_f32_f16_e32 v14, v245
	v_cvt_f32_f16_sdwa v15, v245 dst_sel:DWORD dst_unused:UNUSED_PAD src0_sel:WORD_1
	v_pk_fma_f32 v[14:15], v[14:15], s[34:35], v[16:17] op_sel_hi:[1,0,1]
	s_nop 0
	v_cvt_pk_f16_f32 v25, v14, v15
	global_load_dwordx4 v[14:17], v[28:29], off offset:256
	s_waitcnt vmcnt(0)
	v_cvt_f32_f16_e32 v20, v14
	v_cvt_f32_f16_sdwa v21, v14 dst_sel:DWORD dst_unused:UNUSED_PAD src0_sel:WORD_1
	global_store_dwordx4 v[18:19], v[22:25], off
	v_pk_fma_f32 v[10:11], v[20:21], s[34:35], v[10:11] op_sel_hi:[1,0,1]
	s_nop 0
	v_cvt_pk_f16_f32 v14, v10, v11
	v_cvt_f32_f16_e32 v10, v16
	v_cvt_f32_f16_sdwa v11, v16 dst_sel:DWORD dst_unused:UNUSED_PAD src0_sel:WORD_1
	v_pk_fma_f32 v[6:7], v[10:11], s[34:35], v[6:7] op_sel_hi:[1,0,1]
	s_nop 0
	v_cvt_pk_f16_f32 v16, v6, v7
	v_cvt_f32_f16_e32 v6, v15
	v_cvt_f32_f16_sdwa v7, v15 dst_sel:DWORD dst_unused:UNUSED_PAD src0_sel:WORD_1
	v_pk_fma_f32 v[6:7], v[6:7], s[34:35], v[12:13] op_sel_hi:[1,0,1]
	s_nop 0
	v_cvt_pk_f16_f32 v15, v6, v7
	v_cvt_f32_f16_e32 v6, v17
	v_cvt_f32_f16_sdwa v7, v17 dst_sel:DWORD dst_unused:UNUSED_PAD src0_sel:WORD_1
	v_pk_fma_f32 v[6:7], v[6:7], s[34:35], v[8:9] op_sel_hi:[1,0,1]
	s_nop 0
	v_cvt_pk_f16_f32 v17, v6, v7
	global_store_dwordx4 v[18:19], v[14:17], off offset:256
	s_andn2_b64 vcc, exec, s[6:7]
	s_mov_b64 s[6:7], -1
	s_movk_i32 s26, 0x1fff
	s_cbranch_vccnz .LBB0_167
	s_andn2_b64 vcc, exec, s[0:1]
	s_cbranch_vccnz .LBB0_166
	s_barrier
	s_branch .LBB0_166
